# K-group rescale of the SSD out-projection de-serialised: eight LDS table reads issued up front, one wait, then reciprocals and accumulator multiplies
# speedup vs baseline: 1.0022x; 1.0007x over previous
.LBB0_769:
	s_sub_u32 vcc_lo, s22, s12
	s_subb_u32 vcc_hi, s23, 0
	s_mov_b32 m0, s37
	s_nop 0
	global_load_lds_dwordx4 v214, vcc
	s_mov_b32 m0, s38
	s_nop 0
	global_load_lds_dwordx4 v212, vcc
	ds_read_b128 v[132:135], v231
	ds_read_b128 v[136:139], v231 offset:1024
	ds_read_b128 v[140:143], v231 offset:2048
	ds_read_b128 v[144:147], v231 offset:3072
	ds_read_b128 v[148:151], v231 offset:16384
	ds_read_b128 v[152:155], v231 offset:17408
	ds_read_b128 v[156:159], v231 offset:18432
	ds_read_b128 v[160:163], v231 offset:19456
	ds_read_b128 v[164:167], v197
	ds_read_b128 v[168:171], v197 offset:1024
	ds_read_b128 v[172:175], v197 offset:2048
	ds_read_b128 v[176:179], v197 offset:3072
	ds_read_b128 v[180:183], v197 offset:4096
	ds_read_b128 v[184:187], v197 offset:5120
	ds_read_b128 v[188:191], v197 offset:6144
	ds_read_b128 v[216:219], v197 offset:7168
	s_add_u32 s24, s22, 0x80
	s_addc_u32 s25, s23, 0
	s_add_i32 s57, 0, 0x10000
	s_cmp_eq_u32 s53, s56
	s_cselect_b32 s25, s1, s25
	s_cselect_b32 s24, s0, s24
	s_cselect_b32 s59, s19, s55
	s_cselect_b32 s58, s18, s54
	s_add_i32 s60, 0, 0x14000
	s_add_i32 m0, s33, 0xc000
	s_nop 0
	global_load_lds_dwordx4 v214, s[22:23]
	s_add_i32 m0, s33, 0xe000
	s_nop 0
	global_load_lds_dwordx4 v212, s[22:23]
	s_waitcnt vmcnt(8)
	s_waitcnt lgkmcnt(0)
	v_mfma_f32_16x16x32_bf16 v[126:129], v[132:135], v[164:167], v[126:129]
	v_mfma_f32_16x16x32_bf16 v[126:129], v[136:139], v[168:171], v[126:129]
	s_barrier
	s_setprio 1
	v_mfma_f32_16x16x32_bf16 v[122:125], v[144:147], v[168:171], v[122:125]
	v_mfma_f32_16x16x32_bf16 v[122:125], v[140:143], v[164:167], v[122:125]
	v_mfma_f32_16x16x32_bf16 v[106:109], v[140:143], v[172:175], v[106:109]
	v_mfma_f32_16x16x32_bf16 v[106:109], v[144:147], v[176:179], v[106:109]
	v_mfma_f32_16x16x32_bf16 v[110:113], v[136:139], v[176:179], v[110:113]
	v_mfma_f32_16x16x32_bf16 v[110:113], v[132:135], v[172:175], v[110:113]
	v_mfma_f32_16x16x32_bf16 v[94:97], v[132:135], v[180:183], v[94:97]
	v_mfma_f32_16x16x32_bf16 v[94:97], v[136:139], v[184:187], v[94:97]
	v_mfma_f32_16x16x32_bf16 v[90:93], v[144:147], v[184:187], v[90:93]
	v_mfma_f32_16x16x32_bf16 v[90:93], v[140:143], v[180:183], v[90:93]
	v_mfma_f32_16x16x32_bf16 v[74:77], v[140:143], v[188:191], v[74:77]
	v_mfma_f32_16x16x32_bf16 v[74:77], v[144:147], v[216:219], v[74:77]
	v_mfma_f32_16x16x32_bf16 v[78:81], v[136:139], v[216:219], v[78:81]
	v_mfma_f32_16x16x32_bf16 v[78:81], v[132:135], v[188:191], v[78:81]
	v_mfma_f32_16x16x32_bf16 v[118:121], v[148:151], v[164:167], v[118:121]
	v_mfma_f32_16x16x32_bf16 v[118:121], v[152:155], v[168:171], v[118:121]
	v_mfma_f32_16x16x32_bf16 v[114:117], v[160:163], v[168:171], v[114:117]
	v_mfma_f32_16x16x32_bf16 v[114:117], v[156:159], v[164:167], v[114:117]
	v_mfma_f32_16x16x32_bf16 v[98:101], v[156:159], v[172:175], v[98:101]
	v_mfma_f32_16x16x32_bf16 v[98:101], v[160:163], v[176:179], v[98:101]
	v_mfma_f32_16x16x32_bf16 v[102:105], v[152:155], v[176:179], v[102:105]
	v_mfma_f32_16x16x32_bf16 v[102:105], v[148:151], v[172:175], v[102:105]
	v_mfma_f32_16x16x32_bf16 v[86:89], v[148:151], v[180:183], v[86:89]
	v_mfma_f32_16x16x32_bf16 v[86:89], v[152:155], v[184:187], v[86:89]
	v_mfma_f32_16x16x32_bf16 v[82:85], v[160:163], v[184:187], v[82:85]
	v_mfma_f32_16x16x32_bf16 v[82:85], v[156:159], v[180:183], v[82:85]
	v_mfma_f32_16x16x32_bf16 v[66:69], v[156:159], v[188:191], v[66:69]
	v_mfma_f32_16x16x32_bf16 v[66:69], v[160:163], v[216:219], v[66:69]
	v_mfma_f32_16x16x32_bf16 v[70:73], v[152:155], v[216:219], v[70:73]
	v_mfma_f32_16x16x32_bf16 v[70:73], v[148:151], v[188:191], v[70:73]
	s_setprio 0
	s_barrier
	ds_read_b128 v[164:167], v197 offset:16384
	ds_read_b128 v[168:171], v197 offset:17408
	ds_read_b128 v[172:175], v197 offset:18432
	ds_read_b128 v[176:179], v197 offset:19456
	ds_read_b128 v[180:183], v197 offset:20480
	ds_read_b128 v[184:187], v197 offset:21504
	ds_read_b128 v[188:191], v197 offset:22528
	ds_read_b128 v[216:219], v197 offset:23552
	s_add_i32 s57, s57, s26
	v_lshl_add_u64 v[192:193], s[58:59], 0, v[208:209]
	s_mov_b32 m0, s57
	s_nop 0
	global_load_lds_dwordx4 v208, s[58:59]
	s_add_i32 m0, s57, 0x2000
	v_lshl_add_u64 v[220:221], s[58:59], 0, v[204:205]
	s_add_u32 s58, s58, s12
	s_addc_u32 s59, s59, 0
	s_add_i32 s57, s60, s26
	global_load_lds_dwordx4 v[220:221], off
	v_lshl_add_u64 v[224:225], s[58:59], 0, v[208:209]
	s_mov_b32 m0, s57
	v_lshl_add_u64 v[226:227], s[58:59], 0, v[204:205]
	global_load_lds_dwordx4 v208, s[58:59]
	s_add_i32 m0, s57, 0x2000
	s_nop 0
	global_load_lds_dwordx4 v204, s[58:59]
	s_waitcnt vmcnt(6)
	s_waitcnt lgkmcnt(0)
	v_mfma_f32_16x16x32_bf16 v[62:65], v[132:135], v[164:167], v[62:65]
	v_mfma_f32_16x16x32_bf16 v[62:65], v[136:139], v[168:171], v[62:65]
	s_barrier
	s_setprio 1
	v_mfma_f32_16x16x32_bf16 v[58:61], v[144:147], v[168:171], v[58:61]
	v_mfma_f32_16x16x32_bf16 v[58:61], v[140:143], v[164:167], v[58:61]
	v_mfma_f32_16x16x32_bf16 v[42:45], v[140:143], v[172:175], v[42:45]
	v_mfma_f32_16x16x32_bf16 v[42:45], v[144:147], v[176:179], v[42:45]
	v_mfma_f32_16x16x32_bf16 v[46:49], v[136:139], v[176:179], v[46:49]
	v_mfma_f32_16x16x32_bf16 v[46:49], v[132:135], v[172:175], v[46:49]
	v_mfma_f32_16x16x32_bf16 v[30:33], v[132:135], v[180:183], v[30:33]
	v_mfma_f32_16x16x32_bf16 v[30:33], v[136:139], v[184:187], v[30:33]
	v_mfma_f32_16x16x32_bf16 v[26:29], v[144:147], v[184:187], v[26:29]
	v_mfma_f32_16x16x32_bf16 v[26:29], v[140:143], v[180:183], v[26:29]
	v_mfma_f32_16x16x32_bf16 v[10:13], v[140:143], v[188:191], v[10:13]
	v_mfma_f32_16x16x32_bf16 v[10:13], v[144:147], v[216:219], v[10:13]
	v_mfma_f32_16x16x32_bf16 v[14:17], v[136:139], v[216:219], v[14:17]
	v_mfma_f32_16x16x32_bf16 v[14:17], v[132:135], v[188:191], v[14:17]
	v_mfma_f32_16x16x32_bf16 v[54:57], v[148:151], v[164:167], v[54:57]
	v_mfma_f32_16x16x32_bf16 v[54:57], v[152:155], v[168:171], v[54:57]
	v_mfma_f32_16x16x32_bf16 v[50:53], v[160:163], v[168:171], v[50:53]
	v_mfma_f32_16x16x32_bf16 v[50:53], v[156:159], v[164:167], v[50:53]
	v_mfma_f32_16x16x32_bf16 v[34:37], v[156:159], v[172:175], v[34:37]
	v_mfma_f32_16x16x32_bf16 v[34:37], v[160:163], v[176:179], v[34:37]
	v_mfma_f32_16x16x32_bf16 v[38:41], v[152:155], v[176:179], v[38:41]
	v_mfma_f32_16x16x32_bf16 v[38:41], v[148:151], v[172:175], v[38:41]
	v_mfma_f32_16x16x32_bf16 v[22:25], v[148:151], v[180:183], v[22:25]
	v_mfma_f32_16x16x32_bf16 v[22:25], v[152:155], v[184:187], v[22:25]
	v_mfma_f32_16x16x32_bf16 v[18:21], v[160:163], v[184:187], v[18:21]
	v_mfma_f32_16x16x32_bf16 v[18:21], v[156:159], v[180:183], v[18:21]
	v_mfma_f32_16x16x32_bf16 v[2:5], v[156:159], v[188:191], v[2:5]
	v_mfma_f32_16x16x32_bf16 v[2:5], v[160:163], v[216:219], v[2:5]
	v_mfma_f32_16x16x32_bf16 v[6:9], v[152:155], v[216:219], v[6:9]
	v_mfma_f32_16x16x32_bf16 v[6:9], v[148:151], v[188:191], v[6:9]
	s_setprio 0
	s_barrier
	s_mov_b32 m0, s33
	s_nop 0
	global_load_lds_dwordx4 v210, s[24:25]
	s_mov_b32 m0, s34
	s_nop 0
	global_load_lds_dwordx4 v206, s[24:25]
	ds_read_b128 v[132:135], v231 offset:32768
	ds_read_b128 v[136:139], v231 offset:33792
	ds_read_b128 v[140:143], v231 offset:34816
	ds_read_b128 v[144:147], v231 offset:35840
	ds_read_b128 v[148:151], v231 offset:49152
	ds_read_b128 v[152:155], v231 offset:50176
	ds_read_b128 v[156:159], v231 offset:51200
	ds_read_b128 v[160:163], v231 offset:52224
	ds_read_b128 v[164:167], v197 offset:32768
	ds_read_b128 v[168:171], v197 offset:33792
	ds_read_b128 v[172:175], v197 offset:34816
	ds_read_b128 v[176:179], v197 offset:35840
	ds_read_b128 v[180:183], v197 offset:36864
	ds_read_b128 v[184:187], v197 offset:37888
	ds_read_b128 v[188:191], v197 offset:38912
	ds_read_b128 v[216:219], v197 offset:39936
	s_add_i32 s57, 0, 0x18000
	s_add_i32 s58, 0, 0x1c000
	s_add_u32 s24, s24, s12
	s_addc_u32 s25, s25, 0
	s_mov_b32 m0, s35
	s_nop 0
	global_load_lds_dwordx4 v210, s[24:25]
	s_mov_b32 m0, s36
	s_nop 0
	global_load_lds_dwordx4 v206, s[24:25]
	s_waitcnt vmcnt(8)
	s_waitcnt lgkmcnt(0)
	v_mfma_f32_16x16x32_bf16 v[126:129], v[132:135], v[164:167], v[126:129]
	v_mfma_f32_16x16x32_bf16 v[126:129], v[136:139], v[168:171], v[126:129]
	s_barrier
	s_setprio 1
	v_mfma_f32_16x16x32_bf16 v[122:125], v[144:147], v[168:171], v[122:125]
	v_mfma_f32_16x16x32_bf16 v[122:125], v[140:143], v[164:167], v[122:125]
	v_mfma_f32_16x16x32_bf16 v[106:109], v[140:143], v[172:175], v[106:109]
	v_mfma_f32_16x16x32_bf16 v[106:109], v[144:147], v[176:179], v[106:109]
	v_mfma_f32_16x16x32_bf16 v[110:113], v[136:139], v[176:179], v[110:113]
	v_mfma_f32_16x16x32_bf16 v[110:113], v[132:135], v[172:175], v[110:113]
	v_mfma_f32_16x16x32_bf16 v[94:97], v[132:135], v[180:183], v[94:97]
	v_mfma_f32_16x16x32_bf16 v[94:97], v[136:139], v[184:187], v[94:97]
	v_mfma_f32_16x16x32_bf16 v[90:93], v[144:147], v[184:187], v[90:93]
	v_mfma_f32_16x16x32_bf16 v[90:93], v[140:143], v[180:183], v[90:93]
	v_mfma_f32_16x16x32_bf16 v[74:77], v[140:143], v[188:191], v[74:77]
	v_mfma_f32_16x16x32_bf16 v[74:77], v[144:147], v[216:219], v[74:77]
	v_mfma_f32_16x16x32_bf16 v[78:81], v[136:139], v[216:219], v[78:81]
	v_mfma_f32_16x16x32_bf16 v[78:81], v[132:135], v[188:191], v[78:81]
	v_mfma_f32_16x16x32_bf16 v[118:121], v[148:151], v[164:167], v[118:121]
	v_mfma_f32_16x16x32_bf16 v[118:121], v[152:155], v[168:171], v[118:121]
	v_mfma_f32_16x16x32_bf16 v[114:117], v[160:163], v[168:171], v[114:117]
	v_mfma_f32_16x16x32_bf16 v[114:117], v[156:159], v[164:167], v[114:117]
	v_mfma_f32_16x16x32_bf16 v[98:101], v[156:159], v[172:175], v[98:101]
	v_mfma_f32_16x16x32_bf16 v[98:101], v[160:163], v[176:179], v[98:101]
	v_mfma_f32_16x16x32_bf16 v[102:105], v[152:155], v[176:179], v[102:105]
	v_mfma_f32_16x16x32_bf16 v[102:105], v[148:151], v[172:175], v[102:105]
	v_mfma_f32_16x16x32_bf16 v[86:89], v[148:151], v[180:183], v[86:89]
	v_mfma_f32_16x16x32_bf16 v[86:89], v[152:155], v[184:187], v[86:89]
	v_mfma_f32_16x16x32_bf16 v[82:85], v[160:163], v[184:187], v[82:85]
	v_mfma_f32_16x16x32_bf16 v[82:85], v[156:159], v[180:183], v[82:85]
	v_mfma_f32_16x16x32_bf16 v[66:69], v[156:159], v[188:191], v[66:69]
	v_mfma_f32_16x16x32_bf16 v[66:69], v[160:163], v[216:219], v[66:69]
	v_mfma_f32_16x16x32_bf16 v[70:73], v[152:155], v[216:219], v[70:73]
	v_mfma_f32_16x16x32_bf16 v[70:73], v[148:151], v[188:191], v[70:73]
	s_setprio 0
	s_barrier
	ds_read_b128 v[164:167], v197 offset:49152
	ds_read_b128 v[168:171], v197 offset:50176
	ds_read_b128 v[172:175], v197 offset:51200
	ds_read_b128 v[176:179], v197 offset:52224
	ds_read_b128 v[180:183], v197 offset:53248
	ds_read_b128 v[184:187], v197 offset:54272
	ds_read_b128 v[188:191], v197 offset:55296
	ds_read_b128 v[216:219], v197 offset:56320
	s_add_i32 s24, s57, s26
	v_lshl_add_u64 v[192:193], v[192:193], 0, s[94:95]
	s_mov_b32 m0, s24
	s_nop 0
	global_load_lds_dwordx4 v[192:193], off
	v_lshl_add_u64 v[192:193], v[220:221], 0, s[94:95]
	s_add_i32 m0, s24, 0x2000
	s_add_i32 s24, s58, s26
	global_load_lds_dwordx4 v[192:193], off
	v_lshl_add_u64 v[192:193], v[224:225], 0, s[94:95]
	s_mov_b32 m0, s24
	s_nop 0
	global_load_lds_dwordx4 v[192:193], off
	v_lshl_add_u64 v[192:193], v[226:227], 0, s[94:95]
	s_add_i32 m0, s24, 0x2000
	s_nop 0
	global_load_lds_dwordx4 v[192:193], off
	s_waitcnt vmcnt(6)
	s_waitcnt lgkmcnt(0)
	v_mfma_f32_16x16x32_bf16 v[62:65], v[132:135], v[164:167], v[62:65]
	v_mfma_f32_16x16x32_bf16 v[62:65], v[136:139], v[168:171], v[62:65]
	s_barrier
	s_setprio 1
	v_mfma_f32_16x16x32_bf16 v[58:61], v[144:147], v[168:171], v[58:61]
	v_mfma_f32_16x16x32_bf16 v[58:61], v[140:143], v[164:167], v[58:61]
	v_mfma_f32_16x16x32_bf16 v[42:45], v[140:143], v[172:175], v[42:45]
	v_mfma_f32_16x16x32_bf16 v[42:45], v[144:147], v[176:179], v[42:45]
	v_mfma_f32_16x16x32_bf16 v[46:49], v[136:139], v[176:179], v[46:49]
	v_mfma_f32_16x16x32_bf16 v[46:49], v[132:135], v[172:175], v[46:49]
	v_mfma_f32_16x16x32_bf16 v[30:33], v[132:135], v[180:183], v[30:33]
	v_mfma_f32_16x16x32_bf16 v[30:33], v[136:139], v[184:187], v[30:33]
	v_mfma_f32_16x16x32_bf16 v[26:29], v[144:147], v[184:187], v[26:29]
	v_mfma_f32_16x16x32_bf16 v[26:29], v[140:143], v[180:183], v[26:29]
	v_mfma_f32_16x16x32_bf16 v[10:13], v[140:143], v[188:191], v[10:13]
	v_mfma_f32_16x16x32_bf16 v[10:13], v[144:147], v[216:219], v[10:13]
	v_mfma_f32_16x16x32_bf16 v[14:17], v[136:139], v[216:219], v[14:17]
	v_mfma_f32_16x16x32_bf16 v[14:17], v[132:135], v[188:191], v[14:17]
	v_mfma_f32_16x16x32_bf16 v[54:57], v[148:151], v[164:167], v[54:57]
	v_mfma_f32_16x16x32_bf16 v[54:57], v[152:155], v[168:171], v[54:57]
	v_mfma_f32_16x16x32_bf16 v[50:53], v[160:163], v[168:171], v[50:53]
	v_mfma_f32_16x16x32_bf16 v[50:53], v[156:159], v[164:167], v[50:53]
	v_mfma_f32_16x16x32_bf16 v[34:37], v[156:159], v[172:175], v[34:37]
	v_mfma_f32_16x16x32_bf16 v[34:37], v[160:163], v[176:179], v[34:37]
	v_mfma_f32_16x16x32_bf16 v[38:41], v[152:155], v[176:179], v[38:41]
	v_mfma_f32_16x16x32_bf16 v[38:41], v[148:151], v[172:175], v[38:41]
	v_mfma_f32_16x16x32_bf16 v[22:25], v[148:151], v[180:183], v[22:25]
	v_mfma_f32_16x16x32_bf16 v[22:25], v[152:155], v[184:187], v[22:25]
	v_mfma_f32_16x16x32_bf16 v[18:21], v[160:163], v[184:187], v[18:21]
	v_mfma_f32_16x16x32_bf16 v[18:21], v[156:159], v[180:183], v[18:21]
	v_mfma_f32_16x16x32_bf16 v[2:5], v[156:159], v[188:191], v[2:5]
	v_mfma_f32_16x16x32_bf16 v[2:5], v[160:163], v[216:219], v[2:5]
	v_mfma_f32_16x16x32_bf16 v[6:9], v[152:155], v[216:219], v[6:9]
	v_mfma_f32_16x16x32_bf16 v[6:9], v[148:151], v[188:191], v[6:9]
	s_setprio 0
	s_barrier
	s_and_b32 s24, s56, 6
	s_cmp_eq_u32 s24, 0
	s_cselect_b64 s[58:59], -1, 0
	s_cmp_ge_u32 s56, s53
	s_cselect_b64 s[24:25], -1, 0
	s_cmp_lt_u32 s56, s53
	s_cselect_b64 s[60:61], -1, 0
	s_and_b64 s[58:59], s[58:59], s[60:61]
	s_andn2_b64 vcc, exec, s[58:59]
	s_cbranch_vccnz .LBB0_768
	v_add_u32_e32 v131, 0x400, v130
	v_add_u32_e32 v148, 0x1000, v130
	v_add_u32_e32 v149, 0x1400, v130
	ds_read2_b32 v[132:133], v130 offset1:1
	ds_read2_b32 v[134:135], v130 offset0:128 offset1:129
	ds_read2_b32 v[136:137], v131 offset1:1
	ds_read2_b32 v[138:139], v131 offset0:128 offset1:129
	ds_read2_b32 v[140:141], v148 offset1:1
	ds_read2_b32 v[142:143], v148 offset0:128 offset1:129
	ds_read2_b32 v[144:145], v149 offset1:1
	ds_read2_b32 v[146:147], v149 offset0:128 offset1:129
	s_waitcnt lgkmcnt(0)
	v_rcp_f32_e32 v150, v133
	v_rcp_f32_e32 v151, v135
	v_rcp_f32_e32 v152, v137
	v_rcp_f32_e32 v153, v139
	v_rcp_f32_e32 v154, v141
	v_rcp_f32_e32 v155, v143
	v_rcp_f32_e32 v156, v145
	v_rcp_f32_e32 v157, v147
	v_mul_f32_e32 v132, v132, v150
	v_mul_f32_e32 v134, v134, v151
	v_mul_f32_e32 v136, v136, v152
	v_mul_f32_e32 v138, v138, v153
	v_mul_f32_e32 v140, v140, v154
	v_mul_f32_e32 v142, v142, v155
	v_mul_f32_e32 v144, v144, v156
	v_mul_f32_e32 v146, v146, v157
	v_pk_mul_f32 v[128:129], v[128:129], v[132:133] op_sel_hi:[1,0]
	v_pk_mul_f32 v[126:127], v[126:127], v[132:133] op_sel_hi:[1,0]
	v_pk_mul_f32 v[124:125], v[124:125], v[132:133] op_sel_hi:[1,0]
	v_pk_mul_f32 v[122:123], v[122:123], v[132:133] op_sel_hi:[1,0]
	v_pk_mul_f32 v[120:121], v[120:121], v[132:133] op_sel_hi:[1,0]
	v_pk_mul_f32 v[118:119], v[118:119], v[132:133] op_sel_hi:[1,0]
	v_pk_mul_f32 v[116:117], v[116:117], v[132:133] op_sel_hi:[1,0]
	v_pk_mul_f32 v[114:115], v[114:115], v[132:133] op_sel_hi:[1,0]
	v_pk_mul_f32 v[112:113], v[112:113], v[134:135] op_sel_hi:[1,0]
	v_pk_mul_f32 v[110:111], v[110:111], v[134:135] op_sel_hi:[1,0]
	v_pk_mul_f32 v[108:109], v[108:109], v[134:135] op_sel_hi:[1,0]
	v_pk_mul_f32 v[106:107], v[106:107], v[134:135] op_sel_hi:[1,0]
	v_pk_mul_f32 v[104:105], v[104:105], v[134:135] op_sel_hi:[1,0]
	v_pk_mul_f32 v[102:103], v[102:103], v[134:135] op_sel_hi:[1,0]
	v_pk_mul_f32 v[100:101], v[100:101], v[134:135] op_sel_hi:[1,0]
	v_pk_mul_f32 v[98:99], v[98:99], v[134:135] op_sel_hi:[1,0]
	v_pk_mul_f32 v[96:97], v[96:97], v[136:137] op_sel_hi:[1,0]
	v_pk_mul_f32 v[94:95], v[94:95], v[136:137] op_sel_hi:[1,0]
	v_pk_mul_f32 v[92:93], v[92:93], v[136:137] op_sel_hi:[1,0]
	v_pk_mul_f32 v[90:91], v[90:91], v[136:137] op_sel_hi:[1,0]
	v_pk_mul_f32 v[88:89], v[88:89], v[136:137] op_sel_hi:[1,0]
	v_pk_mul_f32 v[86:87], v[86:87], v[136:137] op_sel_hi:[1,0]
	v_pk_mul_f32 v[84:85], v[84:85], v[136:137] op_sel_hi:[1,0]
	v_pk_mul_f32 v[82:83], v[82:83], v[136:137] op_sel_hi:[1,0]
	v_pk_mul_f32 v[80:81], v[80:81], v[138:139] op_sel_hi:[1,0]
	v_pk_mul_f32 v[78:79], v[78:79], v[138:139] op_sel_hi:[1,0]
	v_pk_mul_f32 v[76:77], v[76:77], v[138:139] op_sel_hi:[1,0]
	v_pk_mul_f32 v[74:75], v[74:75], v[138:139] op_sel_hi:[1,0]
	v_pk_mul_f32 v[72:73], v[72:73], v[138:139] op_sel_hi:[1,0]
	v_pk_mul_f32 v[70:71], v[70:71], v[138:139] op_sel_hi:[1,0]
	v_pk_mul_f32 v[68:69], v[68:69], v[138:139] op_sel_hi:[1,0]
	v_pk_mul_f32 v[66:67], v[66:67], v[138:139] op_sel_hi:[1,0]
	v_pk_mul_f32 v[64:65], v[64:65], v[140:141] op_sel_hi:[1,0]
	v_pk_mul_f32 v[62:63], v[62:63], v[140:141] op_sel_hi:[1,0]
	v_pk_mul_f32 v[60:61], v[60:61], v[140:141] op_sel_hi:[1,0]
	v_pk_mul_f32 v[58:59], v[58:59], v[140:141] op_sel_hi:[1,0]
	v_pk_mul_f32 v[56:57], v[56:57], v[140:141] op_sel_hi:[1,0]
	v_pk_mul_f32 v[54:55], v[54:55], v[140:141] op_sel_hi:[1,0]
	v_pk_mul_f32 v[52:53], v[52:53], v[140:141] op_sel_hi:[1,0]
	v_pk_mul_f32 v[50:51], v[50:51], v[140:141] op_sel_hi:[1,0]
	v_pk_mul_f32 v[48:49], v[48:49], v[142:143] op_sel_hi:[1,0]
	v_pk_mul_f32 v[46:47], v[46:47], v[142:143] op_sel_hi:[1,0]
	v_pk_mul_f32 v[44:45], v[44:45], v[142:143] op_sel_hi:[1,0]
	v_pk_mul_f32 v[42:43], v[42:43], v[142:143] op_sel_hi:[1,0]
	v_pk_mul_f32 v[40:41], v[40:41], v[142:143] op_sel_hi:[1,0]
	v_pk_mul_f32 v[38:39], v[38:39], v[142:143] op_sel_hi:[1,0]
	v_pk_mul_f32 v[36:37], v[36:37], v[142:143] op_sel_hi:[1,0]
	v_pk_mul_f32 v[34:35], v[34:35], v[142:143] op_sel_hi:[1,0]
	v_pk_mul_f32 v[32:33], v[32:33], v[144:145] op_sel_hi:[1,0]
	v_pk_mul_f32 v[30:31], v[30:31], v[144:145] op_sel_hi:[1,0]
	v_pk_mul_f32 v[28:29], v[28:29], v[144:145] op_sel_hi:[1,0]
	v_pk_mul_f32 v[26:27], v[26:27], v[144:145] op_sel_hi:[1,0]
	v_pk_mul_f32 v[24:25], v[24:25], v[144:145] op_sel_hi:[1,0]
	v_pk_mul_f32 v[22:23], v[22:23], v[144:145] op_sel_hi:[1,0]
	v_pk_mul_f32 v[20:21], v[20:21], v[144:145] op_sel_hi:[1,0]
	v_pk_mul_f32 v[18:19], v[18:19], v[144:145] op_sel_hi:[1,0]
	v_pk_mul_f32 v[16:17], v[16:17], v[146:147] op_sel_hi:[1,0]
	v_pk_mul_f32 v[14:15], v[14:15], v[146:147] op_sel_hi:[1,0]
	v_pk_mul_f32 v[12:13], v[12:13], v[146:147] op_sel_hi:[1,0]
	v_pk_mul_f32 v[10:11], v[10:11], v[146:147] op_sel_hi:[1,0]
	v_pk_mul_f32 v[8:9], v[8:9], v[146:147] op_sel_hi:[1,0]
	v_pk_mul_f32 v[6:7], v[6:7], v[146:147] op_sel_hi:[1,0]
	v_pk_mul_f32 v[4:5], v[4:5], v[146:147] op_sel_hi:[1,0]
	v_pk_mul_f32 v[2:3], v[2:3], v[146:147] op_sel_hi:[1,0]
	s_branch .LBB0_768
